# v29 + nontemporal loads of x in the first norm phase (x is read once)
# speedup vs baseline: 1.0061x; 1.0061x over previous
.LBB0_38:
	s_cmpk_lt_i32 s24, 0x4010
	s_cselect_b64 s[78:79], -1, 0
	s_cmpk_gt_i32 s24, 0x400f
	v_mbcnt_lo_u32_b32 v254, -1, 0
	s_waitcnt lgkmcnt(0)
	s_barrier
	s_cbranch_scc1 .LBB0_51
	s_load_dwordx4 s[8:11], s[14:15], 0x0
	s_add_u32 s12, s2, 0x600000
	s_addc_u32 s13, s3, 0
	s_add_i32 s0, s24, 0xffffc000
	s_ashr_i32 s1, s24, 31
	s_cmpk_lt_i32 s24, 0x4000
	s_cselect_b32 s5, s1, 0
	s_cselect_b32 s4, s24, s0
	s_waitcnt lgkmcnt(0)
	s_cselect_b32 s0, s9, s11
	s_cselect_b32 s1, s8, s10
	s_lshl_b64 s[4:5], s[4:5], 14
	s_add_u32 s4, s1, s4
	s_addc_u32 s5, s0, s5
	v_ashrrev_i32_e32 v129, 31, v128
	v_lshl_add_u64 v[28:29], v[128:129], 4, s[4:5]
	s_movk_i32 s20, 0x1000
	s_waitcnt vmcnt(6)
	v_add_co_u32_e32 v64, vcc, s20, v28
	s_movk_i32 s0, 0x2000
	s_waitcnt vmcnt(5)
	v_addc_co_u32_e32 v65, vcc, 0, v29, vcc
	s_waitcnt vmcnt(4)
	v_add_co_u32_e32 v66, vcc, s0, v28
	s_movk_i32 s0, 0x3000
	s_nop 0
	v_addc_co_u32_e32 v67, vcc, 0, v29, vcc
	v_add_co_u32_e32 v68, vcc, s0, v28
	global_load_dwordx4 v[0:3], v[28:29], off nt
	global_load_dwordx4 v[4:7], v[28:29], off offset:1024 nt
	global_load_dwordx4 v[8:11], v[28:29], off offset:2048 nt
	global_load_dwordx4 v[12:15], v[28:29], off offset:3072 nt
	global_load_dwordx4 v[16:19], v[64:65], off offset:1024 nt
	global_load_dwordx4 v[20:23], v[64:65], off offset:2048 nt
	global_load_dwordx4 v[24:27], v[66:67], off nt
	global_load_dwordx4 v[32:35], v[66:67], off offset:1024 nt
	global_load_dwordx4 v[40:43], v[66:67], off offset:2048 nt
	global_load_dwordx4 v[44:47], v[66:67], off offset:3072 nt
	v_addc_co_u32_e32 v69, vcc, 0, v29, vcc
	global_load_dwordx4 v[28:31], v[64:65], off offset:3072 nt
	global_load_dwordx4 v[48:51], v[68:69], off nt
	global_load_dwordx4 v[52:55], v[68:69], off offset:1024 nt
	global_load_dwordx4 v[56:59], v[68:69], off offset:2048 nt
	global_load_dwordx4 v[36:39], v[66:67], off offset:-4096
	global_load_dwordx4 v[60:63], v[68:69], off offset:3072 nt
	v_mbcnt_hi_u32_b32 v64, -1, v254
	v_and_b32_e32 v65, 64, v64
	v_add_u32_e32 v65, 64, v65
	v_xor_b32_e32 v66, 1, v64
	v_cmp_lt_i32_e32 vcc, v66, v65
	s_lshl_b32 s21, s72, 4
	s_movk_i32 s23, 0x7fff
	v_cndmask_b32_e32 v66, v64, v66, vcc
	v_lshlrev_b32_e32 v132, 2, v66
	v_xor_b32_e32 v66, 2, v64
	v_cmp_lt_i32_e32 vcc, v66, v65
	s_mov_b32 s25, 0xffff0000
	v_mov_b32_e32 v138, 0
	v_cndmask_b32_e32 v66, v64, v66, vcc
	v_lshlrev_b32_e32 v133, 2, v66
	v_xor_b32_e32 v66, 4, v64
	v_cmp_lt_i32_e32 vcc, v66, v65
	v_mov_b32_e32 v139, 0x358637bd
	s_mov_b32 s26, 0xf800000
	v_cndmask_b32_e32 v66, v64, v66, vcc
	v_lshlrev_b32_e32 v134, 2, v66
	v_xor_b32_e32 v66, 8, v64
	v_cmp_lt_i32_e32 vcc, v66, v65
	v_mov_b32_e32 v140, 0x260
	s_mov_b32 s14, s24
	v_cndmask_b32_e32 v66, v64, v66, vcc
	v_lshlrev_b32_e32 v135, 2, v66
	v_xor_b32_e32 v66, 16, v64
	v_cmp_lt_i32_e32 vcc, v66, v65
	s_nop 1
	v_cndmask_b32_e32 v66, v64, v66, vcc
	v_lshlrev_b32_e32 v136, 2, v66
	v_xor_b32_e32 v66, 32, v64
	v_cmp_lt_i32_e32 vcc, v66, v65
	s_nop 1
	v_cndmask_b32_e32 v64, v64, v66, vcc
	v_lshlrev_b32_e32 v137, 2, v64
	v_lshl_add_u64 v[64:65], v[128:129], 3, s[2:3]
	s_mov_b64 s[2:3], 0x1f600000
	v_lshl_add_u64 v[130:131], v[64:65], 0, s[2:3]
	v_cmp_eq_u32_e64 s[2:3], 0, v128
	s_branch .LBB0_42

.LBB0_42:
	s_add_i32 s6, s14, s33
	s_cmpk_lt_i32 s6, 0x4010
	s_cselect_b64 s[16:17], -1, 0
	s_cmpk_gt_i32 s6, 0x400f
	s_cbranch_scc1 .LBB0_44
	s_add_i32 s0, s6, 0xffffc000
	s_ashr_i32 s1, s6, 31
	s_cmpk_lt_i32 s6, 0x4000
	s_cselect_b32 s5, s1, 0
	s_cselect_b32 s4, s6, s0
	s_cselect_b32 s0, s9, s11
	s_cselect_b32 s1, s8, s10
	s_lshl_b64 s[4:5], s[4:5], 14
	s_add_u32 s4, s1, s4
	s_addc_u32 s5, s0, s5
	v_lshl_add_u64 v[112:113], v[128:129], 4, s[4:5]
	v_add_co_u32_e32 v96, vcc, s20, v112
	global_load_dwordx4 v[64:67], v[112:113], off nt
	global_load_dwordx4 v[68:71], v[112:113], off offset:1024 nt
	global_load_dwordx4 v[72:75], v[112:113], off offset:2048 nt
	global_load_dwordx4 v[76:79], v[112:113], off offset:3072 nt
	v_addc_co_u32_e32 v97, vcc, 0, v113, vcc
	v_add_co_u32_e32 v108, vcc, 0x2000, v112
	global_load_dwordx4 v[80:83], v[96:97], off nt
	global_load_dwordx4 v[84:87], v[96:97], off offset:1024 nt
	global_load_dwordx4 v[88:91], v[96:97], off offset:2048 nt
	global_load_dwordx4 v[92:95], v[96:97], off offset:3072 nt
	v_addc_co_u32_e32 v109, vcc, 0, v113, vcc
	v_add_co_u32_e32 v124, vcc, 0x3000, v112
	global_load_dwordx4 v[96:99], v[108:109], off nt
	global_load_dwordx4 v[100:103], v[108:109], off offset:1024 nt
	global_load_dwordx4 v[104:107], v[108:109], off offset:2048 nt
	s_nop 0
	global_load_dwordx4 v[108:111], v[108:109], off offset:3072 nt
	v_addc_co_u32_e32 v125, vcc, 0, v113, vcc
	global_load_dwordx4 v[112:115], v[124:125], off nt
	global_load_dwordx4 v[116:119], v[124:125], off offset:1024 nt
	global_load_dwordx4 v[120:123], v[124:125], off offset:2048 nt
	s_nop 0
	global_load_dwordx4 v[124:127], v[124:125], off offset:3072 nt

.LBB0_47:
	s_add_i32 s4, s21, s14
	s_cmpk_gt_i32 s4, 0x400f
	s_cbranch_scc1 .LBB0_49
	s_add_i32 s0, s4, 0xffffc000
	s_ashr_i32 s1, s4, 31
	s_cmpk_lt_i32 s4, 0x4000
	s_cselect_b32 s5, s1, 0
	s_cselect_b32 s4, s4, s0
	s_cselect_b32 s0, s9, s11
	s_cselect_b32 s1, s8, s10
	s_lshl_b64 s[4:5], s[4:5], 14
	s_add_u32 s4, s1, s4
	s_addc_u32 s5, s0, s5
	v_lshl_add_u64 v[48:49], v[128:129], 4, s[4:5]
	v_add_co_u32_e32 v24, vcc, s20, v48
	global_load_dwordx4 v[0:3], v[48:49], off nt
	global_load_dwordx4 v[4:7], v[48:49], off offset:1024 nt
	global_load_dwordx4 v[8:11], v[48:49], off offset:2048 nt
	global_load_dwordx4 v[12:15], v[48:49], off offset:3072 nt
	v_addc_co_u32_e32 v25, vcc, 0, v49, vcc
	v_add_co_u32_e32 v44, vcc, 0x2000, v48
	global_load_dwordx4 v[36:39], v[24:25], off nt
	global_load_dwordx4 v[16:19], v[24:25], off offset:1024 nt
	global_load_dwordx4 v[20:23], v[24:25], off offset:2048 nt
	global_load_dwordx4 v[28:31], v[24:25], off offset:3072 nt
	v_addc_co_u32_e32 v45, vcc, 0, v49, vcc
	v_add_co_u32_e32 v60, vcc, 0x3000, v48
	global_load_dwordx4 v[24:27], v[44:45], off nt
	global_load_dwordx4 v[32:35], v[44:45], off offset:1024 nt
	global_load_dwordx4 v[40:43], v[44:45], off offset:2048 nt
	s_nop 0
	global_load_dwordx4 v[44:47], v[44:45], off offset:3072 nt
	v_addc_co_u32_e32 v61, vcc, 0, v49, vcc
	global_load_dwordx4 v[48:51], v[60:61], off nt
	global_load_dwordx4 v[52:55], v[60:61], off offset:1024 nt
	global_load_dwordx4 v[56:59], v[60:61], off offset:2048 nt
	s_nop 0
	global_load_dwordx4 v[60:63], v[60:61], off offset:3072 nt
